# nt also on hgrn_pre raw q/k loads, residual-row loads of the residual GEMM epilogue, spatial U/V loads, hgrn_prompt V loads
# baseline (speedup 1.0000x reference)
.LBB0_290:
	s_or_b64 exec, exec, s[20:21]
	v_add_u32_e32 v2, s37, v121
	s_bfe_u32 s20, s3, 0x10009
	v_ashrrev_i32_e32 v3, 31, v2
	s_lshl_b32 s38, s20, 18
	s_lshl_b32 s21, s27, 10
	v_lshlrev_b64 v[6:7], 11, v[2:3]
	v_or_b32_e32 v8, 1, v2
	v_or_b32_e32 v10, 2, v2
	v_or_b32_e32 v12, 3, v2
	v_or_b32_e32 v14, 4, v2
	v_or_b32_e32 v16, 5, v2
	v_or_b32_e32 v18, 6, v2
	v_or_b32_e32 v2, 7, v2
	v_lshl_add_u64 v[82:83], v[80:81], 0, s[38:39]
	s_and_b32 s38, s21, 0x400
	v_ashrrev_i32_e32 v3, 31, v2
	v_lshl_add_u64 v[4:5], v[72:73], 0, s[38:39]
	v_ashrrev_i32_e32 v9, 31, v8
	v_ashrrev_i32_e32 v11, 31, v10
	v_ashrrev_i32_e32 v13, 31, v12
	v_ashrrev_i32_e32 v15, 31, v14
	v_ashrrev_i32_e32 v17, 31, v16
	v_ashrrev_i32_e32 v19, 31, v18
	v_lshlrev_b64 v[2:3], 11, v[2:3]
	v_lshl_add_u64 v[6:7], v[4:5], 0, v[6:7]
	v_lshlrev_b64 v[8:9], 11, v[8:9]
	v_lshlrev_b64 v[10:11], 11, v[10:11]
	v_lshlrev_b64 v[12:13], 11, v[12:13]
	v_lshlrev_b64 v[14:15], 11, v[14:15]
	v_lshlrev_b64 v[16:17], 11, v[16:17]
	v_lshlrev_b64 v[18:19], 11, v[18:19]
	v_lshl_add_u64 v[2:3], v[4:5], 0, v[2:3]
	s_waitcnt lgkmcnt(0)
	s_barrier
	v_lshl_add_u64 v[8:9], v[4:5], 0, v[8:9]
	v_lshl_add_u64 v[10:11], v[4:5], 0, v[10:11]
	v_lshl_add_u64 v[12:13], v[4:5], 0, v[12:13]
	v_lshl_add_u64 v[14:15], v[4:5], 0, v[14:15]
	v_lshl_add_u64 v[16:17], v[4:5], 0, v[16:17]
	v_lshl_add_u64 v[18:19], v[4:5], 0, v[18:19]
	global_load_dword v28, v[6:7], off nt
	global_load_dword v30, v[8:9], off nt
	global_load_dword v34, v[10:11], off nt
	global_load_dword v33, v[12:13], off nt
	global_load_dword v51, v[14:15], off nt
	global_load_dword v49, v[16:17], off nt
	global_load_dword v48, v[18:19], off nt
	global_load_dword v50, v[2:3], off nt
	v_add_co_u32_e32 v2, vcc, s31, v6
	s_mov_b32 s21, 0x21000
	s_nop 0
	v_addc_co_u32_e32 v3, vcc, 0, v7, vcc
	v_add_co_u32_e32 v4, vcc, s21, v6
	s_mov_b32 s21, 0x22000
	s_nop 0
	v_addc_co_u32_e32 v5, vcc, 0, v7, vcc
	v_add_co_u32_e32 v8, vcc, s21, v6
	s_mov_b32 s21, 0x23000
	s_nop 0
	v_addc_co_u32_e32 v9, vcc, 0, v7, vcc
	v_add_co_u32_e32 v6, vcc, s21, v6
	s_lshl_b32 s37, s20, 9
	s_nop 0
	v_addc_co_u32_e32 v7, vcc, 0, v7, vcc
	global_load_dword v58, v[4:5], off offset:-4096 nt
	global_load_dword v57, v[2:3], off offset:2048 nt
	global_load_dword v56, v[4:5], off nt
	global_load_dword v55, v[4:5], off offset:2048 nt
	global_load_dword v54, v[6:7], off offset:-4096 nt
	global_load_dword v52, v[6:7], off nt
	global_load_dword v1, v[6:7], off offset:2048 nt
	global_load_dword v53, v[8:9], off offset:2048 nt
	v_or_b32_e32 v2, s37, v120
	v_readlane_b32 s40, v255, 25
	v_lshlrev_b32_e32 v2, 2, v2
	v_mov_b32_e32 v3, v0
	v_readlane_b32 s41, v255, 26
	s_lshr_b32 s21, s27, 1
	s_and_b32 s21, s21, 15
	v_lshl_add_u64 v[84:85], s[40:41], 0, v[2:3]
	v_readlane_b32 s40, v255, 27
	v_readlane_b32 s41, v255, 28
	s_lshl_b32 s21, s21, 7
	v_mov_b32_e32 v125, 0
	v_lshl_add_u64 v[86:87], s[40:41], 0, v[2:3]
	v_add_u32_e32 v2, s37, v70
	v_readlane_b32 s40, v255, 29
	s_lshl_b32 s37, s20, 10
	s_lshl_b32 s20, s20, 11
	v_ashrrev_i32_e32 v3, 31, v2
	v_readlane_b32 s41, v255, 30
	s_cmp_eq_u32 s36, 15
	v_mov_b32_e32 v126, 0
	v_lshl_add_u64 v[88:89], v[2:3], 2, s[40:41]
	s_cselect_b64 s[40:41], -1, 0
	s_add_i32 s21, s21, s28
	v_add_u32_e32 v6, s21, v70
	v_ashrrev_i32_e32 v7, 31, v6
	v_lshlrev_b64 v[6:7], 11, v[6:7]
	v_or_b32_e32 v6, s37, v6
	v_lshl_add_u64 v[90:91], v[76:77], 0, v[6:7]
	v_add_u32_e32 v6, s21, v121
	v_ashrrev_i32_e32 v7, 31, v6
	v_lshl_add_u32 v2, s29, 7, v121
	v_lshlrev_b64 v[6:7], 11, v[6:7]
	v_ashrrev_i32_e32 v3, 31, v2
	v_or_b32_e32 v6, s37, v6
	v_lshlrev_b64 v[4:5], 12, v[2:3]
	v_add_u32_e32 v2, 64, v2
	v_lshl_add_u64 v[92:93], v[78:79], 0, v[6:7]
	v_add_u32_e32 v6, s21, v71
	v_ashrrev_i32_e32 v3, 31, v2
	v_ashrrev_i32_e32 v7, 31, v6
	v_lshlrev_b64 v[2:3], 12, v[2:3]
	v_lshlrev_b64 v[6:7], 11, v[6:7]
	v_or_b32_e32 v6, s37, v6
	v_or_b32_e32 v4, s20, v4
	v_or_b32_e32 v2, s20, v2
	v_lshl_add_u64 v[94:95], v[78:79], 0, v[6:7]
	v_lshl_add_u64 v[96:97], v[74:75], 0, v[4:5]
	v_lshl_add_u64 v[98:99], v[74:75], 0, v[2:3]
	s_mov_b64 s[28:29], 0
	s_mov_b64 s[36:37], 0
	v_mov_b32_e32 v127, 0
	v_mov_b32_e32 v128, 0
	v_mov_b32_e32 v129, 0
	v_mov_b32_e32 v130, 0
	v_mov_b32_e32 v131, 0
	v_mov_b32_e32 v132, 0
	v_mov_b32_e32 v133, 0
	v_mov_b32_e32 v134, 0
	v_mov_b32_e32 v135, 0
	v_mov_b32_e32 v136, 0
	v_mov_b32_e32 v137, 0
	v_mov_b32_e32 v138, 0
	v_mov_b32_e32 v139, 0
	v_mov_b32_e32 v140, 0
	s_branch .LBB0_292

.LBB0_292:
	v_lshl_add_u64 v[234:235], v[84:85], 0, s[28:29]
	v_lshl_add_u64 v[236:237], v[86:87], 0, s[28:29]
	global_load_dwordx2 v[230:231], v[234:235], off
	global_load_dwordx2 v[232:233], v[236:237], off
	v_lshl_add_u64 v[114:115], v[90:91], 0, s[36:37]
	s_mov_b32 s20, 0xc914000
	v_add_co_u32_e32 v2, vcc, s20, v114
	global_load_dwordx4 v[36:39], v[82:83], off offset:-240
	global_load_dwordx4 v[44:47], v[82:83], off offset:-256
	global_load_dwordx4 v[20:23], v[82:83], off offset:-112
	global_load_dwordx4 v[24:27], v[82:83], off offset:-128
	global_load_dwordx4 v[12:15], v[82:83], off offset:16
	global_load_dwordx4 v[16:19], v[82:83], off
	global_load_dwordx4 v[4:7], v[82:83], off offset:144
	global_load_dwordx4 v[8:11], v[82:83], off offset:128
	v_addc_co_u32_e32 v3, vcc, 0, v115, vcc
	global_load_dwordx2 v[118:119], v[2:3], off nt
	global_load_dwordx2 v[116:117], v[2:3], off offset:32 nt
	global_load_dwordx2 v[112:113], v[2:3], off offset:64 nt
	global_load_dwordx2 v[110:111], v[2:3], off offset:96 nt
	global_load_dwordx2 v[108:109], v[2:3], off offset:128 nt
	global_load_dwordx2 v[106:107], v[2:3], off offset:160 nt
	global_load_dwordx2 v[104:105], v[2:3], off offset:192 nt
	global_load_dwordx2 v[102:103], v[2:3], off offset:224 nt
	v_lshl_add_u64 v[2:3], v[88:89], 0, s[28:29]
	global_load_dword v100, v[2:3], off
	s_cmpk_eq_i32 s36, 0x300
	s_cbranch_scc1 .Lsp_lastg
	v_lshl_add_u64 v[2:3], v[92:93], 0, s[36:37]
	v_add_co_u32_e32 v40, vcc, 0xe954000, v2
	s_mov_b32 s20, 0xe954000
	s_nop 0
	v_addc_co_u32_e32 v41, vcc, 0, v3, vcc
	global_load_dword v125, v[40:41], off offset:256 nt
	global_load_dword v126, v[40:41], off offset:2304 nt
	v_add_co_u32_e32 v40, vcc, 0xe955000, v2
	s_nop 1
	v_addc_co_u32_e32 v41, vcc, 0, v3, vcc
	global_load_dword v127, v[40:41], off offset:256 nt
	global_load_dword v128, v[40:41], off offset:2304 nt
	v_add_co_u32_e32 v40, vcc, 0xe956000, v2
	s_nop 1
	v_addc_co_u32_e32 v41, vcc, 0, v3, vcc
	v_add_co_u32_e32 v2, vcc, 0xe957000, v2
	global_load_dword v129, v[40:41], off offset:256 nt
	global_load_dword v130, v[40:41], off offset:2304 nt
	v_addc_co_u32_e32 v3, vcc, 0, v3, vcc
	global_load_dword v131, v[2:3], off offset:256 nt
	global_load_dword v132, v[2:3], off offset:2304 nt
	v_lshl_add_u64 v[2:3], v[94:95], 0, s[36:37]
	v_add_co_u32_e32 v40, vcc, s20, v2
	s_nop 1
	v_addc_co_u32_e32 v41, vcc, 0, v3, vcc
	global_load_dword v133, v[40:41], off offset:256 nt
	global_load_dword v134, v[40:41], off offset:2304 nt
	v_add_co_u32_e32 v40, vcc, 0xe955000, v2
	s_nop 1
	v_addc_co_u32_e32 v41, vcc, 0, v3, vcc
	global_load_dword v135, v[40:41], off offset:256 nt
	global_load_dword v136, v[40:41], off offset:2304 nt
	v_add_co_u32_e32 v40, vcc, 0xe956000, v2
	s_nop 1
	v_addc_co_u32_e32 v41, vcc, 0, v3, vcc
	v_add_co_u32_e32 v2, vcc, 0xe957000, v2
	global_load_dword v137, v[40:41], off offset:256 nt
	global_load_dword v138, v[40:41], off offset:2304 nt
	v_addc_co_u32_e32 v3, vcc, 0, v3, vcc
	global_load_dword v139, v[2:3], off offset:256 nt
	global_load_dword v140, v[2:3], off offset:2304 nt
	s_waitcnt vmcnt(33)
	s_branch .LBB0_294

.LBB0_887:
	s_or_b64 exec, exec, s[4:5]
	v_readlane_b32 s4, v254, 3
	v_readlane_b32 s5, v254, 4
	v_mov_b32_e32 v18, v213
	s_andn2_b64 vcc, exec, s[4:5]
	s_waitcnt lgkmcnt(0)
	s_barrier
	s_cbranch_vccnz .LBB0_898
	v_ashrrev_i32_e32 v1, 3, v18
	v_and_b32_e32 v2, 7, v18
	v_readlane_b32 s3, v254, 6
	v_lshlrev_b32_e32 v24, 4, v2
	v_lshl_add_u32 v22, v2, 5, 0
	v_add_u32_e32 v2, s3, v1
	v_ashrrev_i32_e32 v3, 31, v2
	v_lshlrev_b64 v[2:3], 10, v[2:3]
	v_readlane_b32 s3, v254, 8
	v_readlane_b32 s4, v253, 49
	v_readlane_b32 s5, v253, 50
	v_or_b32_e32 v2, s3, v2
	v_or_b32_e32 v2, v2, v24
	v_lshlrev_b64 v[2:3], 1, v[2:3]
	v_lshl_add_u64 v[4:5], s[4:5], 0, v[2:3]
	v_lshl_add_u64 v[6:7], s[70:71], 0, v[2:3]
	global_load_dwordx4 v[10:13], v[4:5], off offset:16 nt
	global_load_dwordx4 v[14:17], v[4:5], off nt
	s_nop 0
	global_load_dwordx4 v[2:5], v[6:7], off offset:16 nt
	s_nop 0
	global_load_dwordx4 v[6:9], v[6:7], off nt
	v_and_b32_e32 v20, 0x7f, v18
	v_readlane_b32 s3, v254, 52
	v_ashrrev_i32_e32 v21, 6, v18
	s_movk_i32 s20, 0x90
	v_lshl_add_u32 v37, v18, 2, s3
	v_lshl_add_u32 v38, v20, 2, s3
	s_movk_i32 s3, 0x80
	v_cmp_gt_u32_e64 s[10:11], s3, v18
	v_readlane_b32 s3, v254, 53
	v_and_b32_e32 v34, 3, v21
	v_bfe_u32 v23, v18, 4, 2
	v_mov_b32_e32 v28, s3
	v_mad_u32_u24 v35, v20, s20, v28
	v_lshlrev_b32_e32 v28, 4, v34
	s_movk_i32 s18, 0x110
	v_and_b32_e32 v19, 15, v18
	v_lshl_add_u32 v27, v1, 8, v22
	v_lshl_or_b32 v58, v23, 2, v28
	v_lshlrev_b32_e32 v30, 3, v23
	v_lshl_add_u32 v76, v23, 4, 0
	v_mad_u64_u32 v[22:23], s[12:13], v1, s18, v[22:23]
	v_ashrrev_i32_e32 v33, 2, v18
	v_or_b32_e32 v28, v28, v19
	v_add_u32_e32 v40, 0x8000, v22
	v_add_u32_e32 v41, 0x8010, v22
	v_lshlrev_b32_e32 v22, 6, v33
	v_readlane_b32 s12, v254, 11
	v_lshlrev_b32_e32 v29, 5, v34
	v_readlane_b32 s14, v254, 54
	v_mad_u32_u24 v39, v28, s18, v76
	v_ashrrev_i32_e32 v23, 31, v22
	v_readlane_b32 s13, v254, 12
	v_lshlrev_b32_e32 v28, 5, v18
	v_add3_u32 v77, s14, v29, v30
	v_lshl_add_u64 v[22:23], v[22:23], 1, s[12:13]
	v_and_b32_e32 v30, 0x60, v28
	v_mov_b32_e32 v31, v0
	v_lshl_add_u64 v[28:29], v[22:23], 0, v[30:31]
	v_mul_lo_u32 v22, v33, s20
	v_add3_u32 v42, s3, v22, v30
	v_mul_lo_u32 v22, v1, s20
	v_add3_u32 v44, s14, v22, v24
	v_lshlrev_b32_e32 v22, 6, v1
	v_readlane_b32 s12, v254, 9
	v_ashrrev_i32_e32 v23, 31, v22
	v_readlane_b32 s13, v254, 10
	v_mov_b32_e32 v25, v0
	v_ashrrev_i32_e32 v32, 7, v18
	v_lshl_add_u64 v[22:23], v[22:23], 1, s[12:13]
	v_lshl_add_u32 v26, v20, 1, 0
	v_lshl_add_u64 v[30:31], v[22:23], 0, v[24:25]
	v_add_u32_e32 v21, 8, v21
	v_lshl_or_b32 v23, v32, 4, 1
	s_movk_i32 s3, 0x880
	v_lshlrev_b32_e32 v36, 12, v32
	v_cmp_lt_i32_e64 s[4:5], 0, v32
	v_cmp_lt_i32_e64 s[6:7], 1, v32
	v_cmp_lt_i32_e64 s[8:9], 2, v32
	v_lshlrev_b32_e32 v73, 5, v32
	v_ashrrev_i32_e32 v21, 2, v21
	v_mul_lo_u32 v25, v32, s3
	v_mad_u64_u32 v[32:33], s[14:15], v23, s18, v[26:27]
	v_ashrrev_i32_e32 v18, 8, v18
	v_lshl_or_b32 v22, v21, 4, v19
	v_cmp_le_i32_e64 s[14:15], v34, v18
	v_lshl_or_b32 v18, v18, 4, v19
	v_or_b32_e32 v74, 2, v58
	v_or_b32_e32 v75, 3, v58
	v_cmp_gt_i32_e64 s[12:13], v58, v22
	v_lshlrev_b32_e32 v59, 8, v23
	v_or_b32_e32 v25, v25, v20
	v_or_b32_e32 v23, 0x200, v36
	v_or_b32_e32 v60, 0x300, v36
	v_or_b32_e32 v61, 0x400, v36
	v_or_b32_e32 v62, 0x500, v36
	v_or_b32_e32 v63, 0x600, v36
	v_or_b32_e32 v64, 0x700, v36
	v_or_b32_e32 v65, 0x800, v36
	v_or_b32_e32 v66, 0x900, v36
	v_or_b32_e32 v67, 0xa00, v36
	v_or_b32_e32 v68, 0xb00, v36
	v_or_b32_e32 v69, 0xc00, v36
	v_or_b32_e32 v70, 0xd00, v36
	v_or_b32_e32 v71, 0xe00, v36
	v_or_b32_e32 v72, 0xf00, v36
	v_mul_lo_u32 v19, v18, s18
	v_cmp_le_i32_e64 s[16:17], v34, v21
	v_mul_lo_u32 v21, v22, s18
	v_cmp_lt_i32_e64 s[18:19], v58, v22
	v_cmp_gt_i32_e64 s[42:43], v74, v22
	v_cmp_gt_i32_e64 s[44:45], v75, v22
	v_mul_lo_u32 v22, v22, s20
	v_cmp_gt_i32_e64 s[46:47], v58, v18
	v_cmp_lt_i32_e64 s[48:49], v58, v18
	v_cmp_gt_i32_e64 s[50:51], v74, v18
	v_cmp_gt_i32_e64 s[52:53], v75, v18
	v_mul_lo_u32 v18, v18, s20
	v_add_u32_e32 v43, 16, v42
	v_lshl_add_u32 v25, v25, 1, 0
	v_add_u32_e32 v33, 0x110, v32
	v_add_u32_e32 v45, 0x220, v32
	v_add_u32_e32 v46, 0x330, v32
	v_add_u32_e32 v47, 0x440, v32
	v_add_u32_e32 v48, 0x550, v32
	v_add_u32_e32 v49, 0x660, v32
	v_add_u32_e32 v50, 0x770, v32
	v_add_u32_e32 v51, 0x880, v32
	v_add_u32_e32 v52, 0x990, v32
	v_add_u32_e32 v53, 0xaa0, v32
	v_add_u32_e32 v54, 0xbb0, v32
	v_add_u32_e32 v55, 0xcc0, v32
	v_add_u32_e32 v56, 0xdd0, v32
	v_add_u32_e32 v57, 0xee0, v32
	v_lshlrev_b32_e32 v34, 2, v20
	v_add_u32_e32 v58, v26, v59
	v_add_u32_e32 v59, v26, v23
	v_add_u32_e32 v60, v26, v60
	v_add_u32_e32 v61, v26, v61
	v_add_u32_e32 v62, v26, v62
	v_add_u32_e32 v63, v26, v63
	v_add_u32_e32 v64, v26, v64
	v_add_u32_e32 v65, v26, v65
	v_add_u32_e32 v66, v26, v66
	v_add_u32_e32 v67, v26, v67
	v_add_u32_e32 v68, v26, v68
	v_add_u32_e32 v69, v26, v69
	v_add_u32_e32 v70, v26, v70
	v_add_u32_e32 v71, v26, v71
	v_add_u32_e32 v72, v26, v72
	v_add_u32_e32 v73, v35, v73
	v_add_u32_e32 v74, v76, v19
	v_add_u32_e32 v75, v77, v18
	v_add_u32_e32 v76, v76, v21
	v_add_u32_e32 v77, v77, v22
	v_readlane_b32 s3, v254, 7
	v_readlane_b32 s27, v254, 39
	v_readlane_b32 s54, v254, 38
	s_mov_b32 s28, s2
	s_waitcnt vmcnt(0)
	s_branch .LBB0_890

.LBB0_890:
	s_add_i32 s55, s28, s26
	s_cmpk_gt_i32 s55, 0x7ff
	s_cselect_b64 s[20:21], -1, 0
	s_and_b64 vcc, exec, s[20:21]
	s_waitcnt vmcnt(5)
	ds_write_b128 v27, v[6:9]
	ds_write_b128 v27, v[2:5] offset:16
	ds_write_b128 v27, v[14:17] offset:16384
	ds_write_b128 v27, v[10:13] offset:16400
	s_cbranch_vccnz .LBB0_892
	s_and_b32 s29, s54, 0xfffff800
	s_and_b32 s36, s27, 0x7c0
	s_or_b32 s29, s29, s36
	v_add_u32_e32 v2, s29, v1
	v_readlane_b32 s29, v254, 43
	v_ashrrev_i32_e32 v3, 31, v2
	s_add_i32 s29, s29, s3
	v_lshlrev_b64 v[2:3], 10, v[2:3]
	s_and_b32 s29, s29, 0x380
	v_or_b32_e32 v2, s29, v2
	v_or_b32_e32 v2, v2, v24
	v_readlane_b32 s36, v253, 49
	v_lshlrev_b64 v[10:11], 1, v[2:3]
	v_readlane_b32 s37, v253, 50
	v_lshl_add_u64 v[6:7], s[70:71], 0, v[10:11]
	global_load_dwordx4 v[2:5], v[6:7], off offset:16 nt
	s_nop 0
	global_load_dwordx4 v[6:9], v[6:7], off nt
	v_lshl_add_u64 v[14:15], s[36:37], 0, v[10:11]
	global_load_dwordx4 v[10:13], v[14:15], off offset:16 nt
	s_nop 0
	global_load_dwordx4 v[14:17], v[14:15], off nt

.LBB0_949:
	s_lshl_b32 s10, s19, 3
	s_and_b32 s20, s10, 56
	s_ashr_i32 s27, s19, 5
	s_add_i32 s20, s20, s27
	s_ashr_i32 s12, s20, 3
	s_lshl_b32 s28, s12, 11
	v_add_u32_e32 v110, s28, v91
	v_ashrrev_i32_e32 v111, 31, v110
	s_lshl_b32 s14, s20, 5
	s_and_b32 s21, s27, 7
	v_lshlrev_b64 v[2:3], 11, v[110:111]
	s_ashr_i32 s15, s14, 31
	v_lshl_add_u64 v[2:3], s[70:71], 0, v[2:3]
	s_lshl_b32 s38, s21, 8
	s_lshl_b64 s[10:11], s[14:15], 14
	v_lshl_add_u64 v[2:3], v[2:3], 0, s[38:39]
	v_lshlrev_b32_e32 v26, 1, v84
	v_mov_b32_e32 v27, v0
	v_lshl_add_u64 v[14:15], v[86:87], 0, s[10:11]
	s_lshl_b64 s[10:11], s[14:15], 13
	v_lshl_add_u64 v[6:7], v[2:3], 0, v[26:27]
	v_lshl_add_u64 v[18:19], v[88:89], 0, s[10:11]
	global_load_dwordx4 v[2:5], v[6:7], off offset:16
	s_nop 0
	global_load_dwordx4 v[6:9], v[6:7], off
	s_nop 0
	global_load_dwordx4 v[10:13], v[14:15], off offset:16
	s_nop 0
	global_load_dwordx4 v[14:17], v[14:15], off
	v_mov_b32_e32 v1, v0
	global_load_dwordx4 v[18:21], v[18:19], off
	s_bfe_u32 s29, s19, 0x20003
	s_lshl_b32 s15, s21, 7
	v_lshlrev_b32_e32 v66, 1, v90
	v_mov_b64_e32 v[22:23], v[0:1]
	v_mov_b64_e32 v[24:25], v[0:1]
	s_and_saveexec_b64 s[10:11], s[4:5]
	s_cbranch_execz .LBB0_951
	v_add_u32_e32 v22, s28, v132
	v_ashrrev_i32_e32 v23, 31, v22
	v_readlane_b32 s16, v254, 13
	v_lshlrev_b64 v[22:23], 11, v[22:23]
	v_readlane_b32 s17, v254, 14
	s_lshl_b32 s38, s15, 1
	v_mov_b32_e32 v67, v0
	v_lshl_add_u64 v[22:23], s[16:17], 0, v[22:23]
	v_lshl_add_u64 v[22:23], v[22:23], 0, s[38:39]
	s_lshl_b32 s38, s29, 6
	v_lshl_add_u64 v[22:23], v[22:23], 0, s[38:39]
	v_lshl_add_u64 v[22:23], v[22:23], 0, v[66:67]
	global_load_dwordx4 v[22:25], v[22:23], off nt
.LBB0_951:
	s_or_b64 exec, exec, s[10:11]
	s_lshl_b32 s12, s12, 5
	s_ashr_i32 s13, s12, 31
	s_lshl_b64 s[10:11], s[12:13], 12
	v_readlane_b32 s13, v254, 1
	s_add_u32 s16, s13, s10
	v_readlane_b32 s13, v254, 2
	s_addc_u32 s17, s13, s11
	s_lshl_b32 s13, s15, 2
	s_add_u32 s16, s16, s13
	s_addc_u32 s17, s17, 0
	v_lshl_add_u64 v[28:29], v[82:83], 2, s[16:17]
	s_mov_b32 s16, 0x100000
	v_add_co_u32_e32 v30, vcc, s16, v28
	s_or_b32 s36, s28, 64
	s_nop 0
	v_addc_co_u32_e32 v31, vcc, 0, v29, vcc
	global_load_dwordx4 v[62:65], v[28:29], off
	global_load_dwordx4 v[58:61], v[30:31], off
	v_add_u32_e32 v28, s36, v91
	v_ashrrev_i32_e32 v29, 31, v28
	v_lshlrev_b64 v[28:29], 11, v[28:29]
	s_or_b32 s14, s14, 1
	v_lshl_add_u64 v[28:29], s[70:71], 0, v[28:29]
	s_lshl_b32 s38, s15, 1
	s_ashr_i32 s15, s14, 31
	v_lshl_add_u64 v[28:29], v[28:29], 0, s[38:39]
	s_lshl_b64 s[16:17], s[14:15], 14
	s_lshl_b64 s[14:15], s[14:15], 13
	v_lshl_add_u64 v[30:31], v[28:29], 0, v[26:27]
	v_lshl_add_u64 v[38:39], v[86:87], 0, s[16:17]
	v_lshl_add_u64 v[42:43], v[88:89], 0, s[14:15]
	global_load_dwordx4 v[26:29], v[30:31], off offset:16
	s_nop 0
	global_load_dwordx4 v[30:33], v[30:31], off
	s_nop 0
	global_load_dwordx4 v[34:37], v[38:39], off offset:16
	s_nop 0
	global_load_dwordx4 v[38:41], v[38:39], off
	s_nop 0
	global_load_dwordx4 v[42:45], v[42:43], off
	s_and_saveexec_b64 s[14:15], s[6:7]
	s_xor_b64 s[14:15], exec, s[14:15]
	s_lshl_b32 s16, s29, 5
	s_mov_b32 s17, s39
	s_or_saveexec_b64 s[14:15], s[14:15]
	v_mov_b32_e32 v1, v0
	v_mov_b64_e32 v[112:113], s[16:17]
	v_mov_b64_e32 v[46:47], v[0:1]
	v_mov_b64_e32 v[48:49], v[0:1]
	s_xor_b64 exec, exec, s[14:15]
	s_cbranch_execz .LBB0_955
	v_add_u32_e32 v46, s36, v132
	v_ashrrev_i32_e32 v47, 31, v46
	v_readlane_b32 s16, v254, 13
	v_lshlrev_b64 v[46:47], 11, v[46:47]
	v_readlane_b32 s17, v254, 14
	v_mov_b32_e32 v67, v0
	s_nop 0
	v_lshl_add_u64 v[46:47], s[16:17], 0, v[46:47]
	v_lshl_add_u64 v[46:47], v[46:47], 0, s[38:39]
	s_lshl_b32 s16, s29, 6
	s_mov_b32 s17, s39
	v_lshl_add_u64 v[46:47], v[46:47], 0, s[16:17]
	v_lshl_add_u64 v[46:47], v[46:47], 0, v[66:67]
	global_load_dwordx4 v[46:49], v[46:47], off nt
	s_lshl_b32 s16, s29, 5
	v_mov_b64_e32 v[112:113], s[16:17]

.LBB0_960:
	s_or_b64 exec, exec, s[10:11]
	s_waitcnt vmcnt(8)
	v_pk_mul_f32 v[68:69], v[122:123], v[62:63]
	v_pk_mul_f32 v[66:67], v[126:127], v[64:65]
	v_cvt_pk_bf16_f32 v68, v68, v69
	s_cmp_gt_u32 s16, 29
	v_cvt_pk_bf16_f32 v69, v66, v67
	ds_write_b64 v154, v[68:69] offset:49664
	v_pk_mul_f32 v[68:69], v[128:129], v[62:63]
	v_pk_mul_f32 v[66:67], v[124:125], v[64:65]
	v_cvt_pk_bf16_f32 v68, v68, v69
	s_cselect_b64 s[10:11], -1, 0
	v_cvt_pk_bf16_f32 v69, v66, v67
	ds_write_b64 v154, v[68:69] offset:54016
	s_waitcnt lgkmcnt(0)
	s_barrier
	s_and_b64 vcc, exec, s[10:11]
	v_add_u32_e32 v109, s14, v110
	s_cbranch_vccnz .LBB0_964
	s_add_i32 s12, s15, s16
	v_add_u32_e32 v2, 0x80, v109
	s_add_i32 s12, s12, 2
	v_ashrrev_i32_e32 v3, 31, v2
	s_ashr_i32 s13, s12, 31
	v_lshlrev_b64 v[2:3], 11, v[2:3]
	s_lshl_b64 s[28:29], s[12:13], 14
	s_lshl_b64 s[12:13], s[12:13], 13
	v_lshl_add_u64 v[6:7], v[114:115], 0, v[2:3]
	v_lshl_add_u64 v[14:15], v[86:87], 0, s[28:29]
	v_lshl_add_u64 v[18:19], v[88:89], 0, s[12:13]
	global_load_dwordx4 v[2:5], v[6:7], off offset:16
	s_nop 0
	global_load_dwordx4 v[6:9], v[6:7], off
	s_nop 0
	global_load_dwordx4 v[10:13], v[14:15], off offset:16
	s_nop 0
	global_load_dwordx4 v[14:17], v[14:15], off
	s_nop 0
	global_load_dwordx4 v[18:21], v[18:19], off
	s_and_saveexec_b64 s[12:13], s[4:5]
	s_cbranch_execz .LBB0_963
	v_add_u32_e32 v22, s14, v107
	v_add_u32_e32 v22, 0x80, v22
	v_ashrrev_i32_e32 v23, 31, v22
	v_lshlrev_b64 v[22:23], 11, v[22:23]
	v_lshl_add_u64 v[22:23], v[116:117], 0, v[22:23]
	global_load_dwordx4 v[22:25], v[22:23], off nt

.LBB0_967:
	s_or_b64 exec, exec, s[12:13]
	v_pk_mul_f32 v[156:157], v[64:65], v[60:61]
	v_pk_mul_f32 v[158:159], v[62:63], v[58:59]
	v_pk_mul_f32 v[64:65], v[58:59], v[74:75]
	v_pk_mul_f32 v[62:63], v[60:61], v[76:77]
	v_pk_fma_f32 v[64:65], v[122:123], v[158:159], v[64:65]
	v_pk_fma_f32 v[62:63], v[126:127], v[156:157], v[62:63]
	v_pk_mul_f32 v[60:61], v[60:61], v[80:81]
	v_pk_mul_f32 v[74:75], v[58:59], v[78:79]
	s_waitcnt vmcnt(2)
	v_pk_mul_f32 v[76:77], v[54:55], v[64:65]
	v_pk_fma_f32 v[58:59], v[124:125], v[156:157], v[60:61]
	v_pk_fma_f32 v[60:61], v[128:129], v[158:159], v[74:75]
	v_pk_mul_f32 v[74:75], v[56:57], v[62:63]
	v_cvt_pk_bf16_f32 v76, v76, v77
	s_cmp_gt_u32 s16, 28
	v_cvt_pk_bf16_f32 v77, v74, v75
	ds_write_b64 v155, v[76:77]
	v_pk_mul_f32 v[76:77], v[54:55], v[60:61]
	v_pk_mul_f32 v[74:75], v[56:57], v[58:59]
	v_cvt_pk_bf16_f32 v76, v76, v77
	s_nop 0
	v_cvt_pk_bf16_f32 v77, v74, v75
	ds_write_b64 v155, v[76:77] offset:4352
	s_waitcnt lgkmcnt(0)
	s_barrier
	s_cbranch_scc1 .LBB0_970
	s_add_i32 s12, s15, s16
	v_add_u32_e32 v26, 0xc0, v109
	s_add_i32 s12, s12, 3
	v_ashrrev_i32_e32 v27, 31, v26
	s_ashr_i32 s13, s12, 31
	v_lshlrev_b64 v[26:27], 11, v[26:27]
	s_lshl_b64 s[28:29], s[12:13], 14
	s_lshl_b64 s[12:13], s[12:13], 13
	v_lshl_add_u64 v[30:31], v[114:115], 0, v[26:27]
	v_lshl_add_u64 v[38:39], v[86:87], 0, s[28:29]
	v_lshl_add_u64 v[42:43], v[88:89], 0, s[12:13]
	global_load_dwordx4 v[26:29], v[30:31], off offset:16
	s_nop 0
	global_load_dwordx4 v[30:33], v[30:31], off
	s_nop 0
	global_load_dwordx4 v[34:37], v[38:39], off offset:16
	s_nop 0
	global_load_dwordx4 v[38:41], v[38:39], off
	s_nop 0
	global_load_dwordx4 v[42:45], v[42:43], off
	s_and_saveexec_b64 s[12:13], s[4:5]
	s_cbranch_execz .LBB0_956
	v_add_u32_e32 v46, s14, v107
	v_add_u32_e32 v46, 0xc0, v46
	v_ashrrev_i32_e32 v47, 31, v46
	v_lshlrev_b64 v[46:47], 11, v[46:47]
	v_lshl_add_u64 v[46:47], v[116:117], 0, v[46:47]
	global_load_dwordx4 v[46:49], v[46:47], off nt
	s_branch .LBB0_956

.LBB0_1179:
	s_add_i32 s92, s42, 2
	s_add_u32 s72, s36, 0x80
	s_addc_u32 s43, s37, 0
	s_add_i32 s93, 0, 0x10000
	v_add_u32_e32 v1, s93, v223
	ds_read_b128 v[50:53], v1
	ds_read_b128 v[54:57], v1 offset:1024
	ds_read_b128 v[58:61], v1 offset:2048
	ds_read_b128 v[62:65], v1 offset:3072
	s_cmp_eq_u32 s88, s42
	s_cselect_b32 s42, s66, s72
	s_cselect_b32 s43, s67, s43
	s_cselect_b32 s73, s71, s91
	s_cselect_b32 s72, s70, s27
	v_lshl_add_u64 v[178:179], s[36:37], 0, v[206:207]
	s_add_i32 m0, s79, 0xc000
	ds_read_b128 v[66:69], v230
	ds_read_b128 v[70:73], v230 offset:1024
	ds_read_b128 v[74:77], v230 offset:2048
	ds_read_b128 v[78:81], v230 offset:3072
	ds_read_b128 v[146:149], v230 offset:4096
	ds_read_b128 v[154:157], v230 offset:5120
	ds_read_b128 v[170:173], v230 offset:6144
	ds_read_b128 v[174:177], v230 offset:7168
	global_load_lds_dwordx4 v[178:179], off
	v_lshl_add_u64 v[178:179], s[36:37], 0, v[204:205]
	s_add_i32 m0, s79, 0xe000
	s_nop 0
	global_load_lds_dwordx4 v[178:179], off
	s_waitcnt lgkmcnt(8)
	s_barrier
	s_waitcnt lgkmcnt(0)
	s_setprio 1
	s_waitcnt lgkmcnt(0)
	v_mfma_f32_16x16x32_bf16 v[166:169], v[50:53], v[66:69], v[166:169]
	v_mfma_f32_16x16x32_bf16 v[162:165], v[58:61], v[66:69], v[162:165]
	v_mfma_f32_16x16x32_bf16 v[142:145], v[50:53], v[74:77], v[142:145]
	v_mfma_f32_16x16x32_bf16 v[138:141], v[58:61], v[74:77], v[138:141]
	v_mfma_f32_16x16x32_bf16 v[126:129], v[50:53], v[146:149], v[126:129]
	v_mfma_f32_16x16x32_bf16 v[122:125], v[58:61], v[146:149], v[122:125]
	v_mfma_f32_16x16x32_bf16 v[110:113], v[50:53], v[170:173], v[110:113]
	v_mfma_f32_16x16x32_bf16 v[106:109], v[58:61], v[170:173], v[106:109]
	v_mfma_f32_16x16x32_bf16 v[166:169], v[54:57], v[70:73], v[166:169]
	v_mfma_f32_16x16x32_bf16 v[162:165], v[62:65], v[70:73], v[162:165]
	v_mfma_f32_16x16x32_bf16 v[142:145], v[54:57], v[78:81], v[142:145]
	v_mfma_f32_16x16x32_bf16 v[138:141], v[62:65], v[78:81], v[138:141]
	v_mfma_f32_16x16x32_bf16 v[126:129], v[54:57], v[154:157], v[126:129]
	v_mfma_f32_16x16x32_bf16 v[122:125], v[62:65], v[154:157], v[122:125]
	v_mfma_f32_16x16x32_bf16 v[110:113], v[54:57], v[174:177], v[110:113]
	v_mfma_f32_16x16x32_bf16 v[106:109], v[62:65], v[174:177], v[106:109]
	s_setprio 0
	s_barrier
	s_add_i32 s94, 0, 0x14000
	s_add_i32 s93, s93, s78
	v_add_u32_e32 v1, s94, v223
	v_lshl_add_u64 v[214:215], s[72:73], 0, v[202:203]
	s_mov_b32 m0, s93
	ds_read_b128 v[178:181], v1
	ds_read_b128 v[182:185], v1 offset:1024
	ds_read_b128 v[186:189], v1 offset:2048
	ds_read_b128 v[190:193], v1 offset:3072
	global_load_lds_dwordx4 v[214:215], off
	v_lshl_add_u64 v[236:237], s[72:73], 0, v[200:201]
	s_add_i32 m0, s93, 0x2000
	s_nop 0
	global_load_lds_dwordx4 v[236:237], off
	s_barrier
	s_waitcnt lgkmcnt(0)
	s_setprio 1
	s_waitcnt lgkmcnt(0)
	v_mfma_f32_16x16x32_bf16 v[158:161], v[178:181], v[66:69], v[158:161]
	v_mfma_f32_16x16x32_bf16 v[66:69], v[186:189], v[66:69], v[150:153]
	v_mfma_f32_16x16x32_bf16 v[158:161], v[182:185], v[70:73], v[158:161]
	v_mfma_f32_16x16x32_bf16 v[66:69], v[190:193], v[70:73], v[66:69]
	v_mfma_f32_16x16x32_bf16 v[70:73], v[178:181], v[74:77], v[134:137]
	v_mfma_f32_16x16x32_bf16 v[74:77], v[186:189], v[74:77], v[130:133]
	v_mfma_f32_16x16x32_bf16 v[114:117], v[186:189], v[146:149], v[114:117]
	v_mfma_f32_16x16x32_bf16 v[102:105], v[178:181], v[170:173], v[102:105]
	v_mfma_f32_16x16x32_bf16 v[98:101], v[186:189], v[170:173], v[98:101]
	v_mfma_f32_16x16x32_bf16 v[70:73], v[182:185], v[78:81], v[70:73]
	v_mfma_f32_16x16x32_bf16 v[74:77], v[190:193], v[78:81], v[74:77]
	v_mfma_f32_16x16x32_bf16 v[78:81], v[178:181], v[146:149], v[118:121]
	v_mfma_f32_16x16x32_bf16 v[114:117], v[190:193], v[154:157], v[114:117]
	v_mfma_f32_16x16x32_bf16 v[102:105], v[182:185], v[174:177], v[102:105]
	v_mfma_f32_16x16x32_bf16 v[98:101], v[190:193], v[174:177], v[98:101]
	v_mfma_f32_16x16x32_bf16 v[78:81], v[182:185], v[154:157], v[78:81]
	s_setprio 0
	s_mov_b32 m0, s79
	v_lshl_add_u64 v[238:239], s[42:43], 0, v[202:203]
	s_barrier
	ds_read_b128 v[118:121], v230 offset:16384
	ds_read_b128 v[130:133], v230 offset:17408
	ds_read_b128 v[134:137], v230 offset:18432
	ds_read_b128 v[146:149], v230 offset:19456
	ds_read_b128 v[150:153], v230 offset:20480
	ds_read_b128 v[154:157], v230 offset:21504
	ds_read_b128 v[170:173], v230 offset:22528
	ds_read_b128 v[174:177], v230 offset:23552
	global_load_lds_dwordx4 v[238:239], off
	v_lshl_add_u64 v[240:241], s[42:43], 0, v[200:201]
	s_mov_b32 m0, s80
	s_nop 0
	global_load_lds_dwordx4 v[240:241], off
	s_barrier
	s_waitcnt lgkmcnt(0)
	s_setprio 1
	s_waitcnt lgkmcnt(0)
	v_mfma_f32_16x16x32_bf16 v[94:97], v[50:53], v[118:121], v[94:97]
	v_mfma_f32_16x16x32_bf16 v[90:93], v[58:61], v[118:121], v[90:93]
	v_mfma_f32_16x16x32_bf16 v[46:49], v[50:53], v[134:137], v[46:49]
	v_mfma_f32_16x16x32_bf16 v[42:45], v[58:61], v[134:137], v[42:45]
	v_mfma_f32_16x16x32_bf16 v[30:33], v[50:53], v[150:153], v[30:33]
	v_mfma_f32_16x16x32_bf16 v[26:29], v[58:61], v[150:153], v[26:29]
	v_mfma_f32_16x16x32_bf16 v[14:17], v[50:53], v[170:173], v[14:17]
	v_mfma_f32_16x16x32_bf16 v[10:13], v[58:61], v[170:173], v[10:13]
	v_mfma_f32_16x16x32_bf16 v[94:97], v[54:57], v[130:133], v[94:97]
	v_mfma_f32_16x16x32_bf16 v[90:93], v[62:65], v[130:133], v[90:93]
	v_mfma_f32_16x16x32_bf16 v[46:49], v[54:57], v[146:149], v[46:49]
	v_mfma_f32_16x16x32_bf16 v[42:45], v[62:65], v[146:149], v[42:45]
	v_mfma_f32_16x16x32_bf16 v[30:33], v[54:57], v[154:157], v[30:33]
	v_mfma_f32_16x16x32_bf16 v[26:29], v[62:65], v[154:157], v[26:29]
	v_mfma_f32_16x16x32_bf16 v[14:17], v[54:57], v[174:177], v[14:17]
	v_mfma_f32_16x16x32_bf16 v[10:13], v[62:65], v[174:177], v[10:13]
	s_setprio 0
	s_barrier
	s_add_u32 s72, s72, s4
	s_addc_u32 s73, s73, 0
	s_add_i32 s93, s94, s78
	v_lshl_add_u64 v[242:243], s[72:73], 0, v[202:203]
	s_mov_b32 m0, s93
	v_lshl_add_u64 v[244:245], s[72:73], 0, v[200:201]
	global_load_lds_dwordx4 v[242:243], off
	s_add_i32 m0, s93, 0x2000
	s_nop 0
	global_load_lds_dwordx4 v[244:245], off
	s_waitcnt vmcnt(6)
	s_barrier
	s_setprio 1
	v_mfma_f32_16x16x32_bf16 v[38:41], v[178:181], v[134:137], v[38:41]
	v_mfma_f32_16x16x32_bf16 v[34:37], v[186:189], v[134:137], v[34:37]
	v_mfma_f32_16x16x32_bf16 v[22:25], v[178:181], v[150:153], v[22:25]
	v_mfma_f32_16x16x32_bf16 v[18:21], v[186:189], v[150:153], v[18:21]
	v_mfma_f32_16x16x32_bf16 v[6:9], v[178:181], v[170:173], v[6:9]
	v_mfma_f32_16x16x32_bf16 v[2:5], v[186:189], v[170:173], v[2:5]
	v_mfma_f32_16x16x32_bf16 v[50:53], v[178:181], v[118:121], v[86:89]
	v_mfma_f32_16x16x32_bf16 v[54:57], v[186:189], v[118:121], v[82:85]
	v_mfma_f32_16x16x32_bf16 v[38:41], v[182:185], v[146:149], v[38:41]
	v_mfma_f32_16x16x32_bf16 v[34:37], v[190:193], v[146:149], v[34:37]
	v_mfma_f32_16x16x32_bf16 v[22:25], v[182:185], v[154:157], v[22:25]
	v_mfma_f32_16x16x32_bf16 v[18:21], v[190:193], v[154:157], v[18:21]
	v_mfma_f32_16x16x32_bf16 v[6:9], v[182:185], v[174:177], v[6:9]
	v_mfma_f32_16x16x32_bf16 v[2:5], v[190:193], v[174:177], v[2:5]
	v_mfma_f32_16x16x32_bf16 v[50:53], v[182:185], v[130:133], v[50:53]
	v_mfma_f32_16x16x32_bf16 v[54:57], v[190:193], v[130:133], v[54:57]
	s_setprio 0
	s_add_i32 s72, 0, 0x18000
	v_add_u32_e32 v1, s72, v223
	s_barrier
	ds_read_b128 v[58:61], v1
	ds_read_b128 v[62:65], v1 offset:1024
	ds_read_b128 v[82:85], v1 offset:2048
	ds_read_b128 v[86:89], v1 offset:3072
	s_add_u32 s42, s42, s4
	s_addc_u32 s43, s43, 0
	s_mov_b32 m0, s81
	v_lshl_add_u64 v[134:135], s[42:43], 0, v[202:203]
	ds_read_b128 v[118:121], v230 offset:32768
	ds_read_b128 v[130:133], v230 offset:33792
	ds_read_b128 v[146:149], v230 offset:34816
	ds_read_b128 v[154:157], v230 offset:35840
	ds_read_b128 v[170:173], v230 offset:36864
	ds_read_b128 v[174:177], v230 offset:37888
	ds_read_b128 v[178:181], v230 offset:38912
	ds_read_b128 v[182:185], v230 offset:39936
	global_load_lds_dwordx4 v[134:135], off
	v_lshl_add_u64 v[134:135], s[42:43], 0, v[200:201]
	s_mov_b32 m0, s82
	s_nop 0
	global_load_lds_dwordx4 v[134:135], off
	s_waitcnt lgkmcnt(8)
	s_barrier
	s_waitcnt lgkmcnt(0)
	s_setprio 1
	s_waitcnt lgkmcnt(0)
	v_mfma_f32_16x16x32_bf16 v[134:137], v[58:61], v[118:121], v[166:169]
	v_mfma_f32_16x16x32_bf16 v[166:169], v[62:65], v[130:133], v[134:137]
	v_mfma_f32_16x16x32_bf16 v[134:137], v[82:85], v[118:121], v[162:165]
	v_mfma_f32_16x16x32_bf16 v[162:165], v[86:89], v[130:133], v[134:137]
	v_mfma_f32_16x16x32_bf16 v[134:137], v[58:61], v[146:149], v[142:145]
	v_mfma_f32_16x16x32_bf16 v[142:145], v[62:65], v[154:157], v[134:137]
	v_mfma_f32_16x16x32_bf16 v[134:137], v[82:85], v[146:149], v[138:141]
	v_mfma_f32_16x16x32_bf16 v[126:129], v[58:61], v[170:173], v[126:129]
	v_mfma_f32_16x16x32_bf16 v[122:125], v[82:85], v[170:173], v[122:125]
	v_mfma_f32_16x16x32_bf16 v[110:113], v[58:61], v[178:181], v[110:113]
	v_mfma_f32_16x16x32_bf16 v[106:109], v[82:85], v[178:181], v[106:109]
	v_mfma_f32_16x16x32_bf16 v[138:141], v[86:89], v[154:157], v[134:137]
	v_mfma_f32_16x16x32_bf16 v[126:129], v[62:65], v[174:177], v[126:129]
	v_mfma_f32_16x16x32_bf16 v[122:125], v[86:89], v[174:177], v[122:125]
	v_mfma_f32_16x16x32_bf16 v[110:113], v[62:65], v[182:185], v[110:113]
	v_mfma_f32_16x16x32_bf16 v[106:109], v[86:89], v[182:185], v[106:109]
	s_setprio 0
	s_barrier
	s_add_i32 s42, 0, 0x1c000
	s_add_i32 s43, s72, s78
	v_add_u32_e32 v1, s42, v223
	v_lshl_add_u64 v[134:135], v[214:215], 0, s[22:23]
	s_mov_b32 m0, s43
	ds_read_b128 v[186:189], v1
	ds_read_b128 v[190:193], v1 offset:1024
	ds_read_b128 v[208:211], v1 offset:2048
	ds_read_b128 v[232:235], v1 offset:3072
	global_load_lds_dwordx4 v[134:135], off
	v_lshl_add_u64 v[134:135], v[236:237], 0, s[22:23]
	s_add_i32 m0, s43, 0x2000
	s_nop 0
	global_load_lds_dwordx4 v[134:135], off
	s_barrier
	s_waitcnt lgkmcnt(0)
	s_setprio 1
	s_waitcnt lgkmcnt(0)
	v_mfma_f32_16x16x32_bf16 v[66:69], v[208:211], v[118:121], v[66:69]
	v_mfma_f32_16x16x32_bf16 v[134:137], v[186:189], v[118:121], v[158:161]
	v_mfma_f32_16x16x32_bf16 v[150:153], v[232:235], v[130:133], v[66:69]
	v_mfma_f32_16x16x32_bf16 v[66:69], v[186:189], v[146:149], v[70:73]
	v_mfma_f32_16x16x32_bf16 v[158:161], v[190:193], v[130:133], v[134:137]
	v_mfma_f32_16x16x32_bf16 v[134:137], v[190:193], v[154:157], v[66:69]
	v_mfma_f32_16x16x32_bf16 v[66:69], v[208:211], v[146:149], v[74:77]
	v_mfma_f32_16x16x32_bf16 v[130:133], v[232:235], v[154:157], v[66:69]
	v_mfma_f32_16x16x32_bf16 v[66:69], v[186:189], v[170:173], v[78:81]
	v_mfma_f32_16x16x32_bf16 v[118:121], v[190:193], v[174:177], v[66:69]
	v_mfma_f32_16x16x32_bf16 v[66:69], v[208:211], v[170:173], v[114:117]
	v_mfma_f32_16x16x32_bf16 v[114:117], v[232:235], v[174:177], v[66:69]
	v_mfma_f32_16x16x32_bf16 v[66:69], v[186:189], v[178:181], v[102:105]
	v_mfma_f32_16x16x32_bf16 v[102:105], v[190:193], v[182:185], v[66:69]
	v_mfma_f32_16x16x32_bf16 v[66:69], v[208:211], v[178:181], v[98:101]
	v_mfma_f32_16x16x32_bf16 v[98:101], v[232:235], v[182:185], v[66:69]
	s_setprio 0
	s_mov_b32 m0, s86
	v_lshl_add_u64 v[178:179], v[238:239], 0, s[22:23]
	s_barrier
	s_nop 2
	ds_read_b128 v[66:69], v230 offset:49152
	ds_read_b128 v[70:73], v230 offset:50176
	ds_read_b128 v[74:77], v230 offset:51200
	ds_read_b128 v[78:81], v230 offset:52224
	ds_read_b128 v[146:149], v230 offset:53248
	ds_read_b128 v[154:157], v230 offset:54272
	ds_read_b128 v[170:173], v230 offset:55296
	ds_read_b128 v[174:177], v230 offset:56320
	global_load_lds_dwordx4 v[178:179], off
	v_lshl_add_u64 v[178:179], v[240:241], 0, s[22:23]
	s_mov_b32 m0, s87
	s_nop 0
	global_load_lds_dwordx4 v[178:179], off
	s_barrier
	s_waitcnt lgkmcnt(0)
	s_setprio 1
	s_waitcnt lgkmcnt(0)
	v_mfma_f32_16x16x32_bf16 v[94:97], v[58:61], v[66:69], v[94:97]
	v_mfma_f32_16x16x32_bf16 v[90:93], v[82:85], v[66:69], v[90:93]
	v_mfma_f32_16x16x32_bf16 v[46:49], v[58:61], v[74:77], v[46:49]
	v_mfma_f32_16x16x32_bf16 v[42:45], v[82:85], v[74:77], v[42:45]
	v_mfma_f32_16x16x32_bf16 v[30:33], v[58:61], v[146:149], v[30:33]
	v_mfma_f32_16x16x32_bf16 v[26:29], v[82:85], v[146:149], v[26:29]
	v_mfma_f32_16x16x32_bf16 v[14:17], v[58:61], v[170:173], v[14:17]
	v_mfma_f32_16x16x32_bf16 v[10:13], v[82:85], v[170:173], v[10:13]
	v_mfma_f32_16x16x32_bf16 v[94:97], v[62:65], v[70:73], v[94:97]
	v_mfma_f32_16x16x32_bf16 v[90:93], v[86:89], v[70:73], v[90:93]
	v_mfma_f32_16x16x32_bf16 v[46:49], v[62:65], v[78:81], v[46:49]
	v_mfma_f32_16x16x32_bf16 v[42:45], v[86:89], v[78:81], v[42:45]
	v_mfma_f32_16x16x32_bf16 v[30:33], v[62:65], v[154:157], v[30:33]
	v_mfma_f32_16x16x32_bf16 v[26:29], v[86:89], v[154:157], v[26:29]
	v_mfma_f32_16x16x32_bf16 v[14:17], v[62:65], v[174:177], v[14:17]
	v_mfma_f32_16x16x32_bf16 v[10:13], v[86:89], v[174:177], v[10:13]
	s_setprio 0
	s_barrier
	s_add_i32 s42, s42, s78
	v_lshl_add_u64 v[58:59], v[242:243], 0, s[22:23]
	s_mov_b32 m0, s42
	s_nop 0
	global_load_lds_dwordx4 v[58:59], off
	v_lshl_add_u64 v[58:59], v[244:245], 0, s[22:23]
	s_add_i32 m0, s42, 0x2000
	s_nop 0
	global_load_lds_dwordx4 v[58:59], off
	s_waitcnt vmcnt(6)
	s_barrier
	s_setprio 1
	v_mfma_f32_16x16x32_bf16 v[50:53], v[186:189], v[66:69], v[50:53]
	v_mfma_f32_16x16x32_bf16 v[86:89], v[190:193], v[70:73], v[50:53]
	v_mfma_f32_16x16x32_bf16 v[50:53], v[208:211], v[66:69], v[54:57]
	v_mfma_f32_16x16x32_bf16 v[38:41], v[186:189], v[74:77], v[38:41]
	v_mfma_f32_16x16x32_bf16 v[34:37], v[208:211], v[74:77], v[34:37]
	v_mfma_f32_16x16x32_bf16 v[22:25], v[186:189], v[146:149], v[22:25]
	v_mfma_f32_16x16x32_bf16 v[18:21], v[208:211], v[146:149], v[18:21]
	v_mfma_f32_16x16x32_bf16 v[6:9], v[186:189], v[170:173], v[6:9]
	v_mfma_f32_16x16x32_bf16 v[2:5], v[208:211], v[170:173], v[2:5]
	v_mfma_f32_16x16x32_bf16 v[82:85], v[232:235], v[70:73], v[50:53]
	v_mfma_f32_16x16x32_bf16 v[38:41], v[190:193], v[78:81], v[38:41]
	v_mfma_f32_16x16x32_bf16 v[34:37], v[232:235], v[78:81], v[34:37]
	v_mfma_f32_16x16x32_bf16 v[22:25], v[190:193], v[154:157], v[22:25]
	v_mfma_f32_16x16x32_bf16 v[18:21], v[232:235], v[154:157], v[18:21]
	v_mfma_f32_16x16x32_bf16 v[6:9], v[190:193], v[174:177], v[6:9]
	v_mfma_f32_16x16x32_bf16 v[2:5], v[232:235], v[174:177], v[2:5]
	s_setprio 0
	s_add_u32 s27, s27, 0x100
	s_addc_u32 s91, s91, 0
	s_add_u32 s36, s36, 0x100
	s_addc_u32 s37, s37, 0
	s_cmp_ge_u32 s92, s84
	s_mov_b32 s42, s92
	s_barrier
	s_cbranch_scc0 .LBB0_1179
	s_lshl_b32 s3, s3, 8
	s_add_i32 s27, s3, s85
	v_lshl_or_b32 v210, s38, 8, v224
	v_or_b32_e32 v146, s27, v221
	v_ashrrev_i32_e32 v147, 31, v146
	v_ashrrev_i32_e32 v211, 31, v210
	v_lshlrev_b64 v[50:51], 2, v[210:211]
	v_lshl_add_u64 v[208:209], v[210:211], 1, s[48:49]
	v_lshlrev_b64 v[148:149], 11, v[146:147]
	v_lshl_add_u64 v[52:53], s[52:53], 0, v[50:51]
	v_lshl_add_u64 v[54:55], s[54:55], 0, v[50:51]
	v_lshl_add_u64 v[148:149], v[208:209], 0, v[148:149]
	global_load_dwordx4 v[74:77], v[52:53], off
	global_load_dwordx4 v[66:69], v[52:53], off offset:16
	global_load_dwordx4 v[78:81], v[54:55], off
	global_load_dwordx4 v[70:73], v[54:55], off offset:16
	global_load_dwordx4 v[58:61], v[52:53], off offset:512
	s_nop 0
	global_load_dwordx4 v[50:53], v[52:53], off offset:528
	s_nop 0
	global_load_dwordx4 v[62:65], v[54:55], off offset:512
	s_nop 0
	global_load_dwordx4 v[54:57], v[54:55], off offset:528
	global_load_dwordx4 v[190:193], v[148:149], off nt
	global_load_dwordx4 v[186:189], v[148:149], off offset:256 nt
	v_or_b32_e32 v148, 16, v146
	v_ashrrev_i32_e32 v149, 31, v148
	v_lshlrev_b64 v[148:149], 11, v[148:149]
	v_lshl_add_u64 v[148:149], v[208:209], 0, v[148:149]
	global_load_dwordx4 v[182:185], v[148:149], off nt
	global_load_dwordx4 v[178:181], v[148:149], off offset:256 nt
	v_or_b32_e32 v148, 32, v146
	v_or_b32_e32 v146, 48, v146
	v_ashrrev_i32_e32 v149, 31, v148
	v_ashrrev_i32_e32 v147, 31, v146
	v_lshlrev_b64 v[148:149], 11, v[148:149]
	v_lshlrev_b64 v[146:147], 11, v[146:147]
	v_mov_b32_e32 v1, v222
	v_lshl_add_u64 v[148:149], v[208:209], 0, v[148:149]
	v_lshl_add_u64 v[146:147], v[208:209], 0, v[146:147]
	global_load_dwordx4 v[174:177], v[148:149], off nt
	global_load_dwordx4 v[170:173], v[148:149], off offset:256 nt
	global_load_dwordx4 v[154:157], v[146:147], off nt
	s_nop 0
	global_load_dwordx4 v[146:149], v[146:147], off offset:256 nt
	v_cndmask_b32_e64 v211, 0, 1, s[56:57]
	v_cmp_ne_u32_e64 s[42:43], 1, v211
	s_andn2_b64 vcc, exec, s[56:57]
	v_lshl_add_u32 v231, v1, 3, s33
	s_cbranch_vccnz .LBB0_1182
	ds_read_b64 v[214:215], v231
	s_waitcnt lgkmcnt(0)
	v_mov_b32_e32 v212, v215
	s_branch .LBB0_1183

.LBB0_1190:
	s_or_b64 exec, exec, s[36:37]
	v_add_u32_e32 v130, s27, v225
	v_ashrrev_i32_e32 v131, 31, v130
	s_waitcnt lgkmcnt(0)
	v_lshlrev_b64 v[132:133], 11, v[130:131]
	v_or_b32_e32 v130, 16, v130
	v_ashrrev_i32_e32 v131, 31, v130
	v_lshlrev_b64 v[130:131], 11, v[130:131]
	v_mov_b32_e32 v1, v227
	v_lshl_add_u64 v[132:133], v[208:209], 0, v[132:133]
	v_lshl_add_u64 v[130:131], v[208:209], 0, v[130:131]
	global_load_dwordx4 v[142:145], v[132:133], off nt
	global_load_dwordx4 v[138:141], v[132:133], off offset:256 nt
	global_load_dwordx4 v[134:137], v[130:131], off nt
	s_nop 0
	global_load_dwordx4 v[130:133], v[130:131], off offset:256 nt
	s_and_b64 vcc, exec, s[42:43]
	v_lshl_add_u32 v153, v1, 3, s33
	s_cbranch_vccnz .LBB0_1192
	ds_read_b64 v[158:159], v153
	s_waitcnt lgkmcnt(0)
	v_mov_b32_e32 v152, v159
	s_branch .LBB0_1193

.LBB0_1200:
	s_or_b64 exec, exec, s[36:37]
	v_add_u32_e32 v98, s27, v226
	v_ashrrev_i32_e32 v99, 31, v98
	s_waitcnt lgkmcnt(0)
	v_lshlrev_b64 v[100:101], 11, v[98:99]
	v_or_b32_e32 v98, 16, v98
	v_ashrrev_i32_e32 v99, 31, v98
	v_lshlrev_b64 v[98:99], 11, v[98:99]
	v_mov_b32_e32 v1, v228
	v_lshl_add_u64 v[100:101], v[208:209], 0, v[100:101]
	v_lshl_add_u64 v[98:99], v[208:209], 0, v[98:99]
	global_load_dwordx4 v[110:113], v[100:101], off nt
	global_load_dwordx4 v[106:109], v[100:101], off offset:256 nt
	global_load_dwordx4 v[102:105], v[98:99], off nt
	s_nop 0
	global_load_dwordx4 v[98:101], v[98:99], off offset:256 nt
	s_and_b64 vcc, exec, s[42:43]
	v_lshl_add_u32 v117, v1, 3, s33
	s_cbranch_vccnz .LBB0_1202
	ds_read_b64 v[118:119], v117
	s_waitcnt lgkmcnt(0)
	v_mov_b32_e32 v116, v119
	s_branch .LBB0_1203
